# phase 6: row-sum-of-squares values loaded at the tile loop header (before the K-loop) into registers the K-loop leaves free; epilogue starts without a load wait
# speedup vs baseline: 1.0073x; 1.0073x over previous
; template <class Epi, class Sched>
; __device__ __forceinline__ void gemm_phase(PG8_LAS unsigned char* lds, const Gemm g, const Sched& S, const Epi& E) {
;     ...
;     for (;;) {
;         const bool has_next = S.next(ui + 1, nxt);
;         const char* nA = has_next ? (const char*)g.A + (size_t)nxt.pm * tstep : cA; const char* nB = has_next ? (const char*)g.Bt + (size_t)nxt.pn * tstep : cB;
;   __device__ __forceinline__ void operator()(const acc8_t& acc, const pg8::Unit& u, int wr, int wc, int fr, int fq) const {
;     ...
;         const size_t token = EPI_TOKEN(u, ai, m);
;         const float rs = rsqrtf(rss[token] * (1.f / 1024.f) + 1e-6f);
.LBB0_794:
	v_lshl_add_u32 v2, s24, 8, v142
	v_ashrrev_i32_e32 v3, 31, v2
	v_lshl_add_u64 v[2:3], v[2:3], 2, s[12:13]
	global_load_dword v230, v[2:3], off
	global_load_dword v231, v[2:3], off offset:64
	global_load_dword v232, v[2:3], off offset:128
	global_load_dword v233, v[2:3], off offset:192
	global_load_dword v234, v[2:3], off offset:512
	global_load_dword v235, v[2:3], off offset:576
	global_load_dword v236, v[2:3], off offset:640
	global_load_dword v237, v[2:3], off offset:704
	s_add_i32 s50, s50, 1
	s_mul_i32 s15, s50, s0
	s_add_i32 s15, s15, s1
	s_cmp_lt_i32 s15, s3
	s_cselect_b64 s[30:31], -1, 0
	s_cmp_ge_i32 s15, s3
	s_cselect_b64 s[4:5], -1, 0
	s_and_b64 vcc, exec, s[4:5]
	s_cbranch_vccnz .LBB0_799
	s_cmpk_gt_i32 s15, 0x7ff
	s_mov_b64 s[18:19], -1
	s_cbranch_scc0 .LBB0_797
	s_add_i32 s14, s15, 0xfffff800
	s_and_b32 s16, s15, 1
	s_lshr_b32 s14, s14, 1
	s_bitset1_b32 s16, 7
	s_mov_b64 s[18:19], 0

; #define PG8_STAGE(bufoff, gbase, voff) do { _Pragma("unroll") for (int _i = 0; _i < 2; ++_i) \
;         __builtin_amdgcn_global_load_lds((const unsigned*)((const char*)(gbase) + (voff)[_i]), (PG8_LAS unsigned*)(lds + (bufoff) + ldsw + _i * 8192), 16, 0, 0); } while (0)
; #define PG8_LDA(dst, b, h) do { _Pragma("unroll") for (int m = 0; m < 4; ++m) _Pragma("unroll") for (int k = 0; k < 2; ++k) dst[m][k] = *(const PG8_LAS bf16x8*)(lds + PG8_SA(b, h) + aoff + m * 2048 + k * 1024); } while (0)
; #define PG8_LDB(dst, b, h) do { _Pragma("unroll") for (int n = 0; n < 2; ++n) _Pragma("unroll") for (int k = 0; k < 2; ++k) dst[n][k] = *(const PG8_LAS bf16x8*)(lds + PG8_SB(b, h) + boff + n * 2048 + k * 1024); } while (0)
; #define PG8_MMA(ai, bj, At, Bt) do { __builtin_amdgcn_s_setprio(1); _Pragma("unroll") for (int m = 0; m < 4; ++m) _Pragma("unroll") for (int n = 0; n < 2; ++n) _Pragma("unroll") for (int k = 0; k < 2; ++k) \
;         acc[ai][bj][m][n] = __builtin_amdgcn_mfma_f32_16x16x32_bf16(Bt[n][k], At[m][k], acc[ai][bj][m][n], 0, 0, 0); __builtin_amdgcn_s_setprio(0); } while (0)
; #define PG8_WAIT_V(n) asm volatile("s_waitcnt vmcnt(" #n ")" ::: "memory")
; #define PG8_WAIT_L(n) asm volatile("s_waitcnt lgkmcnt(" #n ")" ::: "memory")
; #define PG8_BAR __builtin_amdgcn_s_barrier()
; #define PG8_SCHED __builtin_amdgcn_sched_barrier(0)
; template <class Epi, class Sched>
; __device__ __forceinline__ void gemm_phase(PG8_LAS unsigned char* lds, const Gemm g, const Sched& S, const Epi& E) {
;     ...
;             PG8_LDB(B0, 0, 0); PG8_SCHED; PG8_LDA(At, 0, 0); PG8_STAGE(PG8_SA(1, 1), a1 + hstep, voffA);
;             PG8_WAIT_L(8); PG8_BAR; PG8_WAIT_L(0); PG8_MMA(0, 0, At, B0); PG8_BAR; PG8_SCHED;
;             PG8_LDB(B1, 0, 1); PG8_STAGE(PG8_SB(0, 0), b2, voffB);
;             PG8_BAR; PG8_WAIT_L(0); PG8_MMA(0, 1, At, B1); PG8_BAR;
;             PG8_LDA(At, 0, 1); PG8_STAGE(PG8_SA(0, 0), a2, voffA);
;             PG8_BAR; PG8_WAIT_L(0); PG8_MMA(1, 0, At, B0); PG8_BAR; PG8_SCHED;
;             PG8_STAGE(PG8_SB(0, 1), b2 + hstep, voffB);
;             PG8_WAIT_V(6); PG8_BAR; PG8_MMA(1, 1, At, B1); PG8_BAR;
.LBB0_800:
	ds_read_b128 v[138:141], v145
	ds_read_b128 v[162:165], v146
	ds_read_b128 v[166:169], v147
	ds_read_b128 v[170:173], v148
	s_add_u32 s28, s26, 0xfffc0080
	s_addc_u32 s29, s27, -1
	s_cmp_eq_u32 s58, 12
	s_cselect_b32 s31, s17, s29
	s_cselect_b32 s30, s54, s28
	s_cselect_b32 s29, s15, s57
	s_cselect_b32 s28, s55, s56
	s_mov_b32 m0, s51
	v_lshl_add_u64 v[206:207], s[26:27], 0, v[134:135]
	ds_read_b128 v[174:177], v143
	ds_read_b128 v[178:181], v143 offset:1024
	ds_read_b128 v[182:185], v143 offset:2048
	ds_read_b128 v[186:189], v143 offset:3072
	ds_read_b128 v[190:193], v143 offset:4096
	ds_read_b128 v[194:197], v143 offset:5120
	ds_read_b128 v[198:201], v143 offset:6144
	ds_read_b128 v[202:205], v143 offset:7168
	global_load_lds_dwordx4 v[206:207], off
	v_lshl_add_u64 v[206:207], s[26:27], 0, v[136:137]
	s_mov_b32 m0, s52
	s_nop 0
	global_load_lds_dwordx4 v[206:207], off
	s_waitcnt lgkmcnt(8)
	s_barrier
	s_waitcnt lgkmcnt(0)
	s_setprio 1
	s_waitcnt lgkmcnt(0)
	v_mfma_f32_16x16x32_bf16 v[126:129], v[138:141], v[174:177], v[126:129]
	v_mfma_f32_16x16x32_bf16 v[122:125], v[166:169], v[174:177], v[122:125]
	v_mfma_f32_16x16x32_bf16 v[110:113], v[138:141], v[182:185], v[110:113]
	v_mfma_f32_16x16x32_bf16 v[106:109], v[166:169], v[182:185], v[106:109]
	v_mfma_f32_16x16x32_bf16 v[94:97], v[138:141], v[190:193], v[94:97]
	v_mfma_f32_16x16x32_bf16 v[90:93], v[166:169], v[190:193], v[90:93]
	v_mfma_f32_16x16x32_bf16 v[78:81], v[138:141], v[198:201], v[78:81]
	v_mfma_f32_16x16x32_bf16 v[74:77], v[166:169], v[198:201], v[74:77]
	v_mfma_f32_16x16x32_bf16 v[126:129], v[162:165], v[178:181], v[126:129]
	v_mfma_f32_16x16x32_bf16 v[122:125], v[170:173], v[178:181], v[122:125]
	v_mfma_f32_16x16x32_bf16 v[110:113], v[162:165], v[186:189], v[110:113]
	v_mfma_f32_16x16x32_bf16 v[106:109], v[170:173], v[186:189], v[106:109]
	v_mfma_f32_16x16x32_bf16 v[94:97], v[162:165], v[194:197], v[94:97]
	v_mfma_f32_16x16x32_bf16 v[90:93], v[170:173], v[194:197], v[90:93]
	v_mfma_f32_16x16x32_bf16 v[78:81], v[162:165], v[202:205], v[78:81]
	v_mfma_f32_16x16x32_bf16 v[74:77], v[170:173], v[202:205], v[74:77]
	s_setprio 0
	s_barrier
	s_mov_b32 m0, s23
	v_lshl_add_u64 v[222:223], s[28:29], 0, v[130:131]
	ds_read_b128 v[206:209], v149
	ds_read_b128 v[210:213], v150
	ds_read_b128 v[214:217], v151
	ds_read_b128 v[218:221], v152
	global_load_lds_dwordx4 v[222:223], off
	v_lshl_add_u64 v[224:225], s[28:29], 0, v[132:133]
	s_mov_b32 m0, s25
	s_nop 0
	global_load_lds_dwordx4 v[224:225], off
	s_barrier
	s_waitcnt lgkmcnt(0)
	s_setprio 1
	s_waitcnt lgkmcnt(0)
	v_mfma_f32_16x16x32_bf16 v[118:121], v[206:209], v[174:177], v[118:121]
	v_mfma_f32_16x16x32_bf16 v[114:117], v[214:217], v[174:177], v[114:117]
	v_mfma_f32_16x16x32_bf16 v[102:105], v[206:209], v[182:185], v[102:105]
	v_mfma_f32_16x16x32_bf16 v[98:101], v[214:217], v[182:185], v[98:101]
	v_mfma_f32_16x16x32_bf16 v[86:89], v[206:209], v[190:193], v[86:89]
	v_mfma_f32_16x16x32_bf16 v[82:85], v[214:217], v[190:193], v[82:85]
	v_mfma_f32_16x16x32_bf16 v[70:73], v[206:209], v[198:201], v[70:73]
	v_mfma_f32_16x16x32_bf16 v[66:69], v[214:217], v[198:201], v[66:69]
	v_mfma_f32_16x16x32_bf16 v[118:121], v[210:213], v[178:181], v[118:121]
	v_mfma_f32_16x16x32_bf16 v[114:117], v[218:221], v[178:181], v[114:117]
	v_mfma_f32_16x16x32_bf16 v[102:105], v[210:213], v[186:189], v[102:105]
	v_mfma_f32_16x16x32_bf16 v[98:101], v[218:221], v[186:189], v[98:101]
	v_mfma_f32_16x16x32_bf16 v[86:89], v[210:213], v[194:197], v[86:89]
	v_mfma_f32_16x16x32_bf16 v[82:85], v[218:221], v[194:197], v[82:85]
	v_mfma_f32_16x16x32_bf16 v[70:73], v[210:213], v[202:205], v[70:73]
	v_mfma_f32_16x16x32_bf16 v[66:69], v[218:221], v[202:205], v[66:69]
	s_setprio 0
	s_mov_b32 m0, s38
	v_lshl_add_u64 v[226:227], s[30:31], 0, v[130:131]
	s_barrier
	ds_read_b128 v[174:177], v143 offset:16384
	ds_read_b128 v[178:181], v143 offset:17408
	ds_read_b128 v[182:185], v143 offset:18432
	ds_read_b128 v[186:189], v143 offset:19456
	ds_read_b128 v[190:193], v143 offset:20480
	ds_read_b128 v[194:197], v143 offset:21504
	ds_read_b128 v[198:201], v143 offset:22528
	ds_read_b128 v[202:205], v143 offset:23552
	global_load_lds_dwordx4 v[226:227], off
	v_lshl_add_u64 v[228:229], s[30:31], 0, v[132:133]
	s_mov_b32 m0, s39
	s_nop 0
	global_load_lds_dwordx4 v[228:229], off
	s_barrier
	s_waitcnt lgkmcnt(0)
	s_setprio 1
	s_waitcnt lgkmcnt(0)
	v_mfma_f32_16x16x32_bf16 v[62:65], v[138:141], v[174:177], v[62:65]
	v_mfma_f32_16x16x32_bf16 v[58:61], v[166:169], v[174:177], v[58:61]
	v_mfma_f32_16x16x32_bf16 v[46:49], v[138:141], v[182:185], v[46:49]
	v_mfma_f32_16x16x32_bf16 v[42:45], v[166:169], v[182:185], v[42:45]
	v_mfma_f32_16x16x32_bf16 v[30:33], v[138:141], v[190:193], v[30:33]
	v_mfma_f32_16x16x32_bf16 v[26:29], v[166:169], v[190:193], v[26:29]
	v_mfma_f32_16x16x32_bf16 v[14:17], v[138:141], v[198:201], v[14:17]
	v_mfma_f32_16x16x32_bf16 v[10:13], v[166:169], v[198:201], v[10:13]
	v_mfma_f32_16x16x32_bf16 v[62:65], v[162:165], v[178:181], v[62:65]
	v_mfma_f32_16x16x32_bf16 v[58:61], v[170:173], v[178:181], v[58:61]
	v_mfma_f32_16x16x32_bf16 v[46:49], v[162:165], v[186:189], v[46:49]
	v_mfma_f32_16x16x32_bf16 v[42:45], v[170:173], v[186:189], v[42:45]
	v_mfma_f32_16x16x32_bf16 v[30:33], v[162:165], v[194:197], v[30:33]
	v_mfma_f32_16x16x32_bf16 v[26:29], v[170:173], v[194:197], v[26:29]
	v_mfma_f32_16x16x32_bf16 v[14:17], v[162:165], v[202:205], v[14:17]
	v_mfma_f32_16x16x32_bf16 v[10:13], v[170:173], v[202:205], v[10:13]
	s_setprio 0
	s_barrier
; #define PG8_STAGE(bufoff, gbase, voff) do { _Pragma("unroll") for (int _i = 0; _i < 2; ++_i) \
;         __builtin_amdgcn_global_load_lds((const unsigned*)((const char*)(gbase) + (voff)[_i]), (PG8_LAS unsigned*)(lds + (bufoff) + ldsw + _i * 8192), 16, 0, 0); } while (0)
; #define PG8_LDA(dst, b, h) do { _Pragma("unroll") for (int m = 0; m < 4; ++m) _Pragma("unroll") for (int k = 0; k < 2; ++k) dst[m][k] = *(const PG8_LAS bf16x8*)(lds + PG8_SA(b, h) + aoff + m * 2048 + k * 1024); } while (0)
; #define PG8_LDB(dst, b, h) do { _Pragma("unroll") for (int n = 0; n < 2; ++n) _Pragma("unroll") for (int k = 0; k < 2; ++k) dst[n][k] = *(const PG8_LAS bf16x8*)(lds + PG8_SB(b, h) + boff + n * 2048 + k * 1024); } while (0)
; #define PG8_MMA(ai, bj, At, Bt) do { __builtin_amdgcn_s_setprio(1); _Pragma("unroll") for (int m = 0; m < 4; ++m) _Pragma("unroll") for (int n = 0; n < 2; ++n) _Pragma("unroll") for (int k = 0; k < 2; ++k) \
;         acc[ai][bj][m][n] = __builtin_amdgcn_mfma_f32_16x16x32_bf16(Bt[n][k], At[m][k], acc[ai][bj][m][n], 0, 0, 0); __builtin_amdgcn_s_setprio(0); } while (0)
; #define PG8_WAIT_V(n) asm volatile("s_waitcnt vmcnt(" #n ")" ::: "memory")
; #define PG8_WAIT_L(n) asm volatile("s_waitcnt lgkmcnt(" #n ")" ::: "memory")
; #define PG8_BAR __builtin_amdgcn_s_barrier()
; #define PG8_SCHED __builtin_amdgcn_sched_barrier(0)
; template <class Epi, class Sched>
; __device__ __forceinline__ void gemm_phase(PG8_LAS unsigned char* lds, const Gemm g, const Sched& S, const Epi& E) {
;     ...
;             PG8_WAIT_V(6); PG8_BAR; PG8_MMA(1, 1, At, B1); PG8_BAR;
;             PG8_LDB(B0, 1, 0); PG8_SCHED; PG8_LDA(At, 1, 0); PG8_STAGE(PG8_SA(0, 1), a2 + hstep, voffA);
;             PG8_WAIT_L(8); PG8_BAR; PG8_WAIT_L(0); PG8_MMA(0, 0, At, B0); PG8_BAR; PG8_SCHED;
;             PG8_LDB(B1, 1, 1); PG8_STAGE(PG8_SB(1, 0), b3, voffB);
;             PG8_BAR; PG8_WAIT_L(0); PG8_MMA(0, 1, At, B1); PG8_BAR;
;             PG8_LDA(At, 1, 1); PG8_STAGE(PG8_SA(1, 0), a3, voffA);
;             PG8_BAR; PG8_WAIT_L(0); PG8_MMA(1, 0, At, B0); PG8_BAR; PG8_SCHED;
;             PG8_STAGE(PG8_SB(1, 1), b3 + hstep, voffB);
;             PG8_WAIT_V(6); PG8_BAR; PG8_MMA(1, 1, At, B1); PG8_BAR;
	s_add_u32 s60, s28, 0x40000
	s_addc_u32 s61, s29, 0
	s_mov_b32 m0, s40
	v_lshl_add_u64 v[138:139], s[60:61], 0, v[130:131]
	global_load_lds_dwordx4 v[138:139], off
	v_lshl_add_u64 v[138:139], s[60:61], 0, v[132:133]
	s_mov_b32 m0, s41
	s_nop 0
	global_load_lds_dwordx4 v[138:139], off
	s_waitcnt vmcnt(6)
	s_barrier
	s_setprio 1
	v_mfma_f32_16x16x32_bf16 v[54:57], v[206:209], v[174:177], v[54:57]
	v_mfma_f32_16x16x32_bf16 v[50:53], v[214:217], v[174:177], v[50:53]
	v_mfma_f32_16x16x32_bf16 v[38:41], v[206:209], v[182:185], v[38:41]
	v_mfma_f32_16x16x32_bf16 v[34:37], v[214:217], v[182:185], v[34:37]
	v_mfma_f32_16x16x32_bf16 v[22:25], v[206:209], v[190:193], v[22:25]
	v_mfma_f32_16x16x32_bf16 v[18:21], v[214:217], v[190:193], v[18:21]
	v_mfma_f32_16x16x32_bf16 v[6:9], v[206:209], v[198:201], v[6:9]
	v_mfma_f32_16x16x32_bf16 v[2:5], v[214:217], v[198:201], v[2:5]
	v_mfma_f32_16x16x32_bf16 v[54:57], v[210:213], v[178:181], v[54:57]
	v_mfma_f32_16x16x32_bf16 v[50:53], v[218:221], v[178:181], v[50:53]
	v_mfma_f32_16x16x32_bf16 v[38:41], v[210:213], v[186:189], v[38:41]
	v_mfma_f32_16x16x32_bf16 v[34:37], v[218:221], v[186:189], v[34:37]
	v_mfma_f32_16x16x32_bf16 v[22:25], v[210:213], v[194:197], v[22:25]
	v_mfma_f32_16x16x32_bf16 v[18:21], v[218:221], v[194:197], v[18:21]
	v_mfma_f32_16x16x32_bf16 v[6:9], v[210:213], v[202:205], v[6:9]
	v_mfma_f32_16x16x32_bf16 v[2:5], v[218:221], v[202:205], v[2:5]
	s_setprio 0
	s_barrier
	ds_read_b128 v[138:141], v153
	ds_read_b128 v[162:165], v154
	ds_read_b128 v[166:169], v155
	ds_read_b128 v[170:173], v156
	s_add_u32 s30, s30, 0x40000
	s_addc_u32 s31, s31, 0
	s_mov_b32 m0, s42
	v_lshl_add_u64 v[206:207], s[30:31], 0, v[130:131]
	ds_read_b128 v[174:177], v143 offset:32768
	ds_read_b128 v[178:181], v143 offset:33792
	ds_read_b128 v[182:185], v143 offset:34816
	ds_read_b128 v[186:189], v143 offset:35840
	ds_read_b128 v[190:193], v143 offset:36864
	ds_read_b128 v[194:197], v143 offset:37888
	ds_read_b128 v[198:201], v143 offset:38912
	ds_read_b128 v[202:205], v143 offset:39936
	global_load_lds_dwordx4 v[206:207], off
	v_lshl_add_u64 v[206:207], s[30:31], 0, v[132:133]
	s_mov_b32 m0, s43
	s_nop 0
	global_load_lds_dwordx4 v[206:207], off
	s_waitcnt lgkmcnt(8)
	s_barrier
	s_waitcnt lgkmcnt(0)
	s_setprio 1
	s_waitcnt lgkmcnt(0)
	v_mfma_f32_16x16x32_bf16 v[126:129], v[138:141], v[174:177], v[126:129]
	v_mfma_f32_16x16x32_bf16 v[122:125], v[166:169], v[174:177], v[122:125]
	v_mfma_f32_16x16x32_bf16 v[110:113], v[138:141], v[182:185], v[110:113]
	v_mfma_f32_16x16x32_bf16 v[106:109], v[166:169], v[182:185], v[106:109]
	v_mfma_f32_16x16x32_bf16 v[94:97], v[138:141], v[190:193], v[94:97]
	v_mfma_f32_16x16x32_bf16 v[90:93], v[166:169], v[190:193], v[90:93]
	v_mfma_f32_16x16x32_bf16 v[78:81], v[138:141], v[198:201], v[78:81]
	v_mfma_f32_16x16x32_bf16 v[74:77], v[166:169], v[198:201], v[74:77]
	v_mfma_f32_16x16x32_bf16 v[126:129], v[162:165], v[178:181], v[126:129]
	v_mfma_f32_16x16x32_bf16 v[122:125], v[170:173], v[178:181], v[122:125]
	v_mfma_f32_16x16x32_bf16 v[110:113], v[162:165], v[186:189], v[110:113]
	v_mfma_f32_16x16x32_bf16 v[106:109], v[170:173], v[186:189], v[106:109]
	v_mfma_f32_16x16x32_bf16 v[94:97], v[162:165], v[194:197], v[94:97]
	v_mfma_f32_16x16x32_bf16 v[90:93], v[170:173], v[194:197], v[90:93]
	v_mfma_f32_16x16x32_bf16 v[78:81], v[162:165], v[202:205], v[78:81]
	v_mfma_f32_16x16x32_bf16 v[74:77], v[170:173], v[202:205], v[74:77]
	s_setprio 0
	s_barrier
	s_mov_b32 m0, s44
	v_lshl_add_u64 v[222:223], v[222:223], 0, s[8:9]
	ds_read_b128 v[206:209], v157
	ds_read_b128 v[210:213], v158
	ds_read_b128 v[214:217], v159
	ds_read_b128 v[218:221], v160
	global_load_lds_dwordx4 v[222:223], off
	v_lshl_add_u64 v[222:223], v[224:225], 0, s[8:9]
	s_mov_b32 m0, s45
	s_nop 0
	global_load_lds_dwordx4 v[222:223], off
	s_barrier
	s_waitcnt lgkmcnt(0)
	s_setprio 1
	s_waitcnt lgkmcnt(0)
	v_mfma_f32_16x16x32_bf16 v[118:121], v[206:209], v[174:177], v[118:121]
	v_mfma_f32_16x16x32_bf16 v[114:117], v[214:217], v[174:177], v[114:117]
	v_mfma_f32_16x16x32_bf16 v[102:105], v[206:209], v[182:185], v[102:105]
	v_mfma_f32_16x16x32_bf16 v[98:101], v[214:217], v[182:185], v[98:101]
	v_mfma_f32_16x16x32_bf16 v[86:89], v[206:209], v[190:193], v[86:89]
	v_mfma_f32_16x16x32_bf16 v[82:85], v[214:217], v[190:193], v[82:85]
	v_mfma_f32_16x16x32_bf16 v[70:73], v[206:209], v[198:201], v[70:73]
	v_mfma_f32_16x16x32_bf16 v[66:69], v[214:217], v[198:201], v[66:69]
	v_mfma_f32_16x16x32_bf16 v[118:121], v[210:213], v[178:181], v[118:121]
	v_mfma_f32_16x16x32_bf16 v[114:117], v[218:221], v[178:181], v[114:117]
	v_mfma_f32_16x16x32_bf16 v[102:105], v[210:213], v[186:189], v[102:105]
	v_mfma_f32_16x16x32_bf16 v[98:101], v[218:221], v[186:189], v[98:101]
	v_mfma_f32_16x16x32_bf16 v[86:89], v[210:213], v[194:197], v[86:89]
	v_mfma_f32_16x16x32_bf16 v[82:85], v[218:221], v[194:197], v[82:85]
	v_mfma_f32_16x16x32_bf16 v[70:73], v[210:213], v[202:205], v[70:73]
	v_mfma_f32_16x16x32_bf16 v[66:69], v[218:221], v[202:205], v[66:69]
	s_setprio 0
	s_mov_b32 m0, s46
	v_lshl_add_u64 v[222:223], v[226:227], 0, s[8:9]
	s_barrier
	ds_read_b128 v[174:177], v143 offset:49152
	ds_read_b128 v[178:181], v143 offset:50176
	ds_read_b128 v[182:185], v143 offset:51200
	ds_read_b128 v[186:189], v143 offset:52224
	ds_read_b128 v[190:193], v143 offset:53248
	ds_read_b128 v[194:197], v143 offset:54272
	ds_read_b128 v[198:201], v143 offset:55296
	ds_read_b128 v[202:205], v143 offset:56320
	global_load_lds_dwordx4 v[222:223], off
	v_lshl_add_u64 v[222:223], v[228:229], 0, s[8:9]
	s_mov_b32 m0, s47
	s_nop 0
	global_load_lds_dwordx4 v[222:223], off
	s_barrier
;   __device__ __forceinline__ void operator()(const acc8_t& acc, const pg8::Unit& u, int wr, int wc, int fr, int fq) const {
;     ...
; #pragma unroll
;     for (int ai = 0; ai < 2; ai++)
; #pragma unroll
;       for (int m = 0; m < 4; m++) {
;         const size_t token = EPI_TOKEN(u, ai, m);
;         const float rs = rsqrtf(rss[token] * (1.f / 1024.f) + 1e-6f);
; #pragma unroll
;         for (int bj = 0; bj < 2; bj++)
; #pragma unroll
;           for (int n = 0; n < 2; n++) {
;             const int f = EPI_COL(u, bj, n);
;             const float v0 = fmaxf(acc[ai][bj][m][n][0] * rs, 0.f), v1 = fmaxf(acc[ai][bj][m][n][1] * rs, 0.f);
;             const float v2 = fmaxf(acc[ai][bj][m][n][2] * rs, 0.f), v3 = fmaxf(acc[ai][bj][m][n][3] * rs, 0.f);
;             uint2 o; o.x = pack2(v0 * v0, v1 * v1); o.y = pack2(v2 * v2, v3 * v3);
;             *(uint2*)(H + token * 4096 + f) = o;
;           }
	s_waitcnt lgkmcnt(0)
	s_setprio 1
	s_waitcnt lgkmcnt(0)
	v_mfma_f32_16x16x32_bf16 v[62:65], v[138:141], v[174:177], v[62:65]
	v_mfma_f32_16x16x32_bf16 v[58:61], v[166:169], v[174:177], v[58:61]
	v_mfma_f32_16x16x32_bf16 v[46:49], v[138:141], v[182:185], v[46:49]
	v_mfma_f32_16x16x32_bf16 v[42:45], v[166:169], v[182:185], v[42:45]
	v_mfma_f32_16x16x32_bf16 v[30:33], v[138:141], v[190:193], v[30:33]
	v_mfma_f32_16x16x32_bf16 v[26:29], v[166:169], v[190:193], v[26:29]
	v_mfma_f32_16x16x32_bf16 v[14:17], v[138:141], v[198:201], v[14:17]
	v_mfma_f32_16x16x32_bf16 v[10:13], v[166:169], v[198:201], v[10:13]
	v_mfma_f32_16x16x32_bf16 v[62:65], v[162:165], v[178:181], v[62:65]
	v_mfma_f32_16x16x32_bf16 v[58:61], v[170:173], v[178:181], v[58:61]
	v_mfma_f32_16x16x32_bf16 v[46:49], v[162:165], v[186:189], v[46:49]
	v_mfma_f32_16x16x32_bf16 v[42:45], v[170:173], v[186:189], v[42:45]
	v_mfma_f32_16x16x32_bf16 v[30:33], v[162:165], v[194:197], v[30:33]
	v_mfma_f32_16x16x32_bf16 v[26:29], v[170:173], v[194:197], v[26:29]
	v_mfma_f32_16x16x32_bf16 v[14:17], v[162:165], v[202:205], v[14:17]
	v_mfma_f32_16x16x32_bf16 v[10:13], v[170:173], v[202:205], v[10:13]
	s_setprio 0
	s_barrier
	s_add_u32 s28, s28, 0x40080
	s_addc_u32 s29, s29, 0
	s_mov_b32 m0, s48
	v_lshl_add_u64 v[138:139], s[28:29], 0, v[130:131]
	global_load_lds_dwordx4 v[138:139], off
	v_lshl_add_u64 v[138:139], s[28:29], 0, v[132:133]
	s_mov_b32 m0, s49
	s_nop 0
	global_load_lds_dwordx4 v[138:139], off
	s_waitcnt vmcnt(6)
	s_barrier
	s_setprio 1
	v_mfma_f32_16x16x32_bf16 v[54:57], v[206:209], v[174:177], v[54:57]
	v_mfma_f32_16x16x32_bf16 v[50:53], v[214:217], v[174:177], v[50:53]
	v_mfma_f32_16x16x32_bf16 v[38:41], v[206:209], v[182:185], v[38:41]
	v_mfma_f32_16x16x32_bf16 v[34:37], v[214:217], v[182:185], v[34:37]
	v_mfma_f32_16x16x32_bf16 v[22:25], v[206:209], v[190:193], v[22:25]
	v_mfma_f32_16x16x32_bf16 v[18:21], v[214:217], v[190:193], v[18:21]
	v_mfma_f32_16x16x32_bf16 v[6:9], v[206:209], v[198:201], v[6:9]
	v_mfma_f32_16x16x32_bf16 v[2:5], v[214:217], v[198:201], v[2:5]
	v_mfma_f32_16x16x32_bf16 v[54:57], v[210:213], v[178:181], v[54:57]
	v_mfma_f32_16x16x32_bf16 v[50:53], v[218:221], v[178:181], v[50:53]
	v_mfma_f32_16x16x32_bf16 v[38:41], v[210:213], v[186:189], v[38:41]
	v_mfma_f32_16x16x32_bf16 v[34:37], v[218:221], v[186:189], v[34:37]
	v_mfma_f32_16x16x32_bf16 v[22:25], v[210:213], v[194:197], v[22:25]
	v_mfma_f32_16x16x32_bf16 v[18:21], v[218:221], v[194:197], v[18:21]
	v_mfma_f32_16x16x32_bf16 v[6:9], v[210:213], v[202:205], v[6:9]
	v_mfma_f32_16x16x32_bf16 v[2:5], v[218:221], v[202:205], v[2:5]
	s_setprio 0
	s_add_i32 s58, s58, 2
	s_add_u32 s26, s26, 0x100
	s_addc_u32 s27, s27, 0
	s_add_u32 s56, s56, 0x100
	s_addc_u32 s57, s57, 0
	s_cmp_gt_u32 s58, 13
	s_barrier
	s_cbranch_scc0 .LBB0_800
	v_lshl_add_u32 v140, s24, 8, v142
	v_ashrrev_i32_e32 v141, 31, v140
	v_lshl_add_u64 v[138:139], v[140:141], 2, s[12:13]
	v_mov_b32_e32 v166, v230
	v_mov_b32_e32 v176, v231
	v_mov_b32_e32 v177, v232
	v_mov_b32_e32 v178, v233
	v_mov_b32_e32 v179, v234
	v_mov_b32_e32 v180, v235
	v_mov_b32_e32 v181, v236
	v_mov_b32_e32 v182, v237
	v_lshlrev_b64 v[164:165], 13, v[140:141]
	v_lshl_or_b32 v138, s22, 8, v144
	v_ashrrev_i32_e32 v139, 31, v138
	v_or_b32_e32 v162, 16, v140
	v_lshlrev_b64 v[138:139], 1, v[138:139]
	v_bfe_u32 v183, v0, 4, 1
	v_mul_u32_u24_e32 v183, 24, v183
	v_add_u32_e32 v138, v138, v183
	v_lshl_add_u64 v[164:165], s[10:11], 0, v[164:165]
	v_ashrrev_i32_e32 v163, 31, v162
	v_lshl_add_u64 v[164:165], v[164:165], 0, v[138:139]
	s_mov_b32 s22, s14
	s_mov_b32 s24, s16
	s_mov_b64 s[28:29], s[20:21]
	s_mov_b64 s[26:27], s[18:19]
	v_fmamk_f32 v141, v166, 0x3a800000, v161
	v_mul_f32_e32 v166, 0x4b800000, v141
	v_cmp_gt_f32_e32 vcc, s53, v141
	s_nop 1
	v_cndmask_b32_e32 v141, v141, v166, vcc
	v_rsq_f32_e32 v141, v141
	v_lshl_add_u64 v[166:167], v[162:163], 2, s[12:13]
	v_mul_f32_e32 v168, 0x45800000, v141
	v_cndmask_b32_e32 v141, v141, v168, vcc
	v_mul_f32_e32 v126, v126, v141
	v_mul_f32_e32 v127, v127, v141
	v_mul_f32_e32 v128, v128, v141
	v_mul_f32_e32 v129, v129, v141
	v_mul_f32_e32 v122, v122, v141
	v_mul_f32_e32 v123, v123, v141
	v_mul_f32_e32 v124, v124, v141
	v_mul_f32_e32 v125, v125, v141
	v_mul_f32_e32 v168, v118, v141
	v_mul_f32_e32 v169, v119, v141
	v_mul_f32_e32 v170, v120, v141
	v_mul_f32_e32 v171, v121, v141
	v_mul_f32_e32 v172, v114, v141
	v_mul_f32_e32 v173, v115, v141
	v_mul_f32_e32 v174, v116, v141
	v_mul_f32_e32 v141, v117, v141
	v_max_f32_e32 v114, 0, v126
	v_max_f32_e32 v115, 0, v127
	v_max_f32_e32 v116, 0, v128
	v_max_f32_e32 v117, 0, v129
	v_max_f32_e32 v118, 0, v122
	v_max_f32_e32 v119, 0, v123
	v_max_f32_e32 v120, 0, v124
	v_max_f32_e32 v121, 0, v125
	v_max_f32_e32 v122, 0, v168
	v_max_f32_e32 v123, 0, v169
	v_max_f32_e32 v124, 0, v170
	v_max_f32_e32 v125, 0, v171
	v_max_f32_e32 v126, 0, v172
	v_max_f32_e32 v127, 0, v173
	v_max_f32_e32 v128, 0, v174
	v_max_f32_e32 v129, 0, v141
	v_pk_mul_f32 v[114:115], v[114:115], v[114:115]
	v_pk_mul_f32 v[116:117], v[116:117], v[116:117]
	v_pk_mul_f32 v[118:119], v[118:119], v[118:119]
	v_pk_mul_f32 v[120:121], v[120:121], v[120:121]
	v_pk_mul_f32 v[122:123], v[122:123], v[122:123]
	v_pk_mul_f32 v[124:125], v[124:125], v[124:125]
	v_pk_mul_f32 v[126:127], v[126:127], v[126:127]
	v_pk_mul_f32 v[128:129], v[128:129], v[128:129]
	v_cvt_pk_bf16_f32 v114, v114, v115
	v_cvt_pk_bf16_f32 v115, v116, v117
	v_cvt_pk_bf16_f32 v116, v118, v119
	v_cvt_pk_bf16_f32 v117, v120, v121
	v_cvt_pk_bf16_f32 v118, v122, v123
	v_cvt_pk_bf16_f32 v119, v124, v125
	v_cvt_pk_bf16_f32 v120, v126, v127
	v_cvt_pk_bf16_f32 v121, v128, v129
	v_permlane16_swap_b32_e32 v114, v116
;   __device__ __forceinline__ void operator()(const acc8_t& acc, const pg8::Unit& u, int wr, int wc, int fr, int fq) const {
;     ...
;         const size_t token = EPI_TOKEN(u, ai, m);
;         const float rs = rsqrtf(rss[token] * (1.f / 1024.f) + 1e-6f);
; #pragma unroll
;         for (int bj = 0; bj < 2; bj++)
; #pragma unroll
;           for (int n = 0; n < 2; n++) {
;             const int f = EPI_COL(u, bj, n);
;             const float v0 = fmaxf(acc[ai][bj][m][n][0] * rs, 0.f), v1 = fmaxf(acc[ai][bj][m][n][1] * rs, 0.f);
;             const float v2 = fmaxf(acc[ai][bj][m][n][2] * rs, 0.f), v3 = fmaxf(acc[ai][bj][m][n][3] * rs, 0.f);
;             uint2 o; o.x = pack2(v0 * v0, v1 * v1); o.y = pack2(v2 * v2, v3 * v3);
;             *(uint2*)(H + token * 4096 + f) = o;
	v_permlane16_swap_b32_e32 v115, v117
	v_permlane16_swap_b32_e32 v118, v120
	v_permlane16_swap_b32_e32 v119, v121
	global_store_dwordx4 v[164:165], v[114:117], off
	global_store_dwordx4 v[164:165], v[118:121], off offset:256
	s_nop 1
	v_mov_b32_e32 v118, v176
	v_lshlrev_b64 v[116:117], 13, v[162:163]
	v_or_b32_e32 v114, 32, v140
	v_lshl_add_u64 v[116:117], s[10:11], 0, v[116:117]
	v_ashrrev_i32_e32 v115, 31, v114
	v_lshl_add_u64 v[116:117], v[116:117], 0, v[138:139]
	v_fmamk_f32 v118, v118, 0x3a800000, v161
	v_mul_f32_e32 v119, 0x4b800000, v118
	v_cmp_gt_f32_e32 vcc, s53, v118
	s_nop 1
	v_cndmask_b32_e32 v118, v118, v119, vcc
	v_rsq_f32_e32 v120, v118
	v_lshl_add_u64 v[118:119], v[114:115], 2, s[12:13]
	v_mul_f32_e32 v121, 0x45800000, v120
	v_cndmask_b32_e32 v120, v120, v121, vcc
	v_mul_f32_e32 v110, v110, v120
	v_mul_f32_e32 v111, v111, v120
	v_mul_f32_e32 v112, v112, v120
	v_mul_f32_e32 v113, v113, v120
	v_mul_f32_e32 v106, v106, v120
	v_mul_f32_e32 v107, v107, v120
	v_mul_f32_e32 v108, v108, v120
	v_mul_f32_e32 v109, v109, v120
	v_mul_f32_e32 v121, v102, v120
	v_mul_f32_e32 v122, v103, v120
	v_mul_f32_e32 v123, v104, v120
	v_mul_f32_e32 v124, v105, v120
	v_mul_f32_e32 v125, v98, v120
	v_mul_f32_e32 v126, v99, v120
	v_mul_f32_e32 v127, v100, v120
	v_mul_f32_e32 v120, v101, v120
	v_max_f32_e32 v98, 0, v110
	v_max_f32_e32 v99, 0, v111
	v_max_f32_e32 v100, 0, v112
	v_max_f32_e32 v101, 0, v113
	v_max_f32_e32 v102, 0, v106
	v_max_f32_e32 v103, 0, v107
	v_max_f32_e32 v104, 0, v108
	v_max_f32_e32 v105, 0, v109
	v_max_f32_e32 v106, 0, v121
	v_max_f32_e32 v107, 0, v122
	v_max_f32_e32 v108, 0, v123
	v_max_f32_e32 v109, 0, v124
	v_max_f32_e32 v110, 0, v125
	v_max_f32_e32 v111, 0, v126
	v_max_f32_e32 v112, 0, v127
	v_max_f32_e32 v113, 0, v120
	v_pk_mul_f32 v[98:99], v[98:99], v[98:99]
	v_pk_mul_f32 v[100:101], v[100:101], v[100:101]
	v_pk_mul_f32 v[102:103], v[102:103], v[102:103]
	v_pk_mul_f32 v[104:105], v[104:105], v[104:105]
	v_pk_mul_f32 v[106:107], v[106:107], v[106:107]
	v_pk_mul_f32 v[108:109], v[108:109], v[108:109]
	v_pk_mul_f32 v[110:111], v[110:111], v[110:111]
	v_pk_mul_f32 v[112:113], v[112:113], v[112:113]
	v_cvt_pk_bf16_f32 v98, v98, v99
	v_cvt_pk_bf16_f32 v99, v100, v101
	v_cvt_pk_bf16_f32 v100, v102, v103
	v_cvt_pk_bf16_f32 v101, v104, v105
	v_cvt_pk_bf16_f32 v102, v106, v107
	v_cvt_pk_bf16_f32 v103, v108, v109
	v_cvt_pk_bf16_f32 v104, v110, v111
	v_cvt_pk_bf16_f32 v105, v112, v113
	v_permlane16_swap_b32_e32 v98, v100
	v_permlane16_swap_b32_e32 v99, v101
	v_permlane16_swap_b32_e32 v102, v104
	v_permlane16_swap_b32_e32 v103, v105
	global_store_dwordx4 v[116:117], v[98:101], off
	global_store_dwordx4 v[116:117], v[102:105], off offset:256
	s_nop 1
	v_mov_b32_e32 v102, v177
	v_lshlrev_b64 v[100:101], 13, v[114:115]
	v_or_b32_e32 v98, 48, v140
	v_lshl_add_u64 v[100:101], s[10:11], 0, v[100:101]
	v_ashrrev_i32_e32 v99, 31, v98
	v_lshl_add_u64 v[100:101], v[100:101], 0, v[138:139]
	v_fmamk_f32 v102, v102, 0x3a800000, v161
	v_mul_f32_e32 v103, 0x4b800000, v102
	v_cmp_gt_f32_e32 vcc, s53, v102
	s_nop 1
	v_cndmask_b32_e32 v102, v102, v103, vcc
	v_rsq_f32_e32 v104, v102
	v_lshl_add_u64 v[102:103], v[98:99], 2, s[12:13]
	v_mul_f32_e32 v105, 0x45800000, v104
	v_cndmask_b32_e32 v104, v104, v105, vcc
	v_mul_f32_e32 v94, v94, v104
	v_mul_f32_e32 v95, v95, v104
	v_mul_f32_e32 v96, v96, v104
	v_mul_f32_e32 v97, v97, v104
	v_mul_f32_e32 v90, v90, v104
	v_mul_f32_e32 v91, v91, v104
	v_mul_f32_e32 v92, v92, v104
	v_mul_f32_e32 v93, v93, v104
	v_mul_f32_e32 v105, v86, v104
	v_mul_f32_e32 v106, v87, v104
	v_mul_f32_e32 v107, v88, v104
	v_mul_f32_e32 v108, v89, v104
	v_mul_f32_e32 v109, v82, v104
	v_mul_f32_e32 v110, v83, v104
	v_mul_f32_e32 v111, v84, v104
	v_mul_f32_e32 v104, v85, v104
	v_max_f32_e32 v82, 0, v94
	v_max_f32_e32 v83, 0, v95
	v_max_f32_e32 v84, 0, v96
	v_max_f32_e32 v85, 0, v97
	v_max_f32_e32 v86, 0, v90
	v_max_f32_e32 v87, 0, v91
	v_max_f32_e32 v88, 0, v92
	v_max_f32_e32 v89, 0, v93
	v_max_f32_e32 v90, 0, v105
	v_max_f32_e32 v91, 0, v106
	v_max_f32_e32 v92, 0, v107
	v_max_f32_e32 v93, 0, v108
	v_max_f32_e32 v94, 0, v109
	v_max_f32_e32 v95, 0, v110
	v_max_f32_e32 v96, 0, v111
	v_max_f32_e32 v97, 0, v104
	v_pk_mul_f32 v[82:83], v[82:83], v[82:83]
	v_pk_mul_f32 v[84:85], v[84:85], v[84:85]
	v_pk_mul_f32 v[86:87], v[86:87], v[86:87]
	v_pk_mul_f32 v[88:89], v[88:89], v[88:89]
	v_pk_mul_f32 v[90:91], v[90:91], v[90:91]
	v_pk_mul_f32 v[92:93], v[92:93], v[92:93]
	v_pk_mul_f32 v[94:95], v[94:95], v[94:95]
	v_pk_mul_f32 v[96:97], v[96:97], v[96:97]
	v_cvt_pk_bf16_f32 v82, v82, v83
	v_cvt_pk_bf16_f32 v83, v84, v85
	v_cvt_pk_bf16_f32 v84, v86, v87
	v_cvt_pk_bf16_f32 v85, v88, v89
	v_cvt_pk_bf16_f32 v86, v90, v91
	v_cvt_pk_bf16_f32 v87, v92, v93
	v_cvt_pk_bf16_f32 v88, v94, v95
	v_cvt_pk_bf16_f32 v89, v96, v97
	v_permlane16_swap_b32_e32 v82, v84
	v_permlane16_swap_b32_e32 v83, v85
	v_permlane16_swap_b32_e32 v86, v88
	v_permlane16_swap_b32_e32 v87, v89
	global_store_dwordx4 v[100:101], v[82:85], off
	global_store_dwordx4 v[100:101], v[86:89], off offset:256
	s_nop 1
	v_mov_b32_e32 v86, v178
	v_lshlrev_b64 v[84:85], 13, v[98:99]
	v_add_u32_e32 v82, 0x80, v140
	v_lshl_add_u64 v[84:85], s[10:11], 0, v[84:85]
	v_ashrrev_i32_e32 v83, 31, v82
	v_lshl_add_u64 v[84:85], v[84:85], 0, v[138:139]
	v_fmamk_f32 v86, v86, 0x3a800000, v161
	v_mul_f32_e32 v87, 0x4b800000, v86
	v_cmp_gt_f32_e32 vcc, s53, v86
	s_nop 1
	v_cndmask_b32_e32 v86, v86, v87, vcc
	v_rsq_f32_e32 v88, v86
	v_lshl_add_u64 v[86:87], v[82:83], 2, s[12:13]
	v_mul_f32_e32 v89, 0x45800000, v88
	v_cndmask_b32_e32 v88, v88, v89, vcc
	v_mul_f32_e32 v78, v78, v88
	v_mul_f32_e32 v79, v79, v88
;   __device__ __forceinline__ void operator()(const acc8_t& acc, const pg8::Unit& u, int wr, int wc, int fr, int fq) const {
;     ...
;         const size_t token = EPI_TOKEN(u, ai, m);
;         const float rs = rsqrtf(rss[token] * (1.f / 1024.f) + 1e-6f);
; #pragma unroll
;         for (int bj = 0; bj < 2; bj++)
; #pragma unroll
;           for (int n = 0; n < 2; n++) {
;             const int f = EPI_COL(u, bj, n);
;             const float v0 = fmaxf(acc[ai][bj][m][n][0] * rs, 0.f), v1 = fmaxf(acc[ai][bj][m][n][1] * rs, 0.f);
;             const float v2 = fmaxf(acc[ai][bj][m][n][2] * rs, 0.f), v3 = fmaxf(acc[ai][bj][m][n][3] * rs, 0.f);
;             uint2 o; o.x = pack2(v0 * v0, v1 * v1); o.y = pack2(v2 * v2, v3 * v3);
;             *(uint2*)(H + token * 4096 + f) = o;
	v_mul_f32_e32 v80, v80, v88
	v_mul_f32_e32 v81, v81, v88
	v_mul_f32_e32 v74, v74, v88
	v_mul_f32_e32 v75, v75, v88
	v_mul_f32_e32 v76, v76, v88
	v_mul_f32_e32 v77, v77, v88
	v_mul_f32_e32 v89, v70, v88
	v_mul_f32_e32 v90, v71, v88
	v_mul_f32_e32 v91, v72, v88
	v_mul_f32_e32 v92, v73, v88
	v_mul_f32_e32 v93, v66, v88
	v_mul_f32_e32 v94, v67, v88
	v_mul_f32_e32 v95, v68, v88
	v_mul_f32_e32 v88, v69, v88
	v_max_f32_e32 v66, 0, v78
	v_max_f32_e32 v67, 0, v79
	v_max_f32_e32 v68, 0, v80
	v_max_f32_e32 v69, 0, v81
	v_max_f32_e32 v70, 0, v74
	v_max_f32_e32 v71, 0, v75
	v_max_f32_e32 v72, 0, v76
	v_max_f32_e32 v73, 0, v77
	v_max_f32_e32 v74, 0, v89
	v_max_f32_e32 v75, 0, v90
	v_max_f32_e32 v76, 0, v91
	v_max_f32_e32 v77, 0, v92
	v_max_f32_e32 v78, 0, v93
	v_max_f32_e32 v79, 0, v94
	v_max_f32_e32 v80, 0, v95
	v_max_f32_e32 v81, 0, v88
	v_pk_mul_f32 v[66:67], v[66:67], v[66:67]
	v_pk_mul_f32 v[68:69], v[68:69], v[68:69]
	v_pk_mul_f32 v[70:71], v[70:71], v[70:71]
	v_pk_mul_f32 v[72:73], v[72:73], v[72:73]
	v_pk_mul_f32 v[74:75], v[74:75], v[74:75]
	v_pk_mul_f32 v[76:77], v[76:77], v[76:77]
	v_pk_mul_f32 v[78:79], v[78:79], v[78:79]
	v_pk_mul_f32 v[80:81], v[80:81], v[80:81]
	v_cvt_pk_bf16_f32 v66, v66, v67
	v_cvt_pk_bf16_f32 v67, v68, v69
	v_cvt_pk_bf16_f32 v68, v70, v71
	v_cvt_pk_bf16_f32 v69, v72, v73
	v_cvt_pk_bf16_f32 v70, v74, v75
	v_cvt_pk_bf16_f32 v71, v76, v77
	v_cvt_pk_bf16_f32 v72, v78, v79
	v_cvt_pk_bf16_f32 v73, v80, v81
	v_permlane16_swap_b32_e32 v66, v68
	v_permlane16_swap_b32_e32 v67, v69
	v_permlane16_swap_b32_e32 v70, v72
	v_permlane16_swap_b32_e32 v71, v73
	global_store_dwordx4 v[84:85], v[66:69], off
	global_store_dwordx4 v[84:85], v[70:73], off offset:256
	s_nop 1
	v_mov_b32_e32 v70, v179
	v_lshlrev_b64 v[68:69], 13, v[82:83]
	v_add_u32_e32 v66, 0x90, v140
	v_lshl_add_u64 v[68:69], s[10:11], 0, v[68:69]
	v_ashrrev_i32_e32 v67, 31, v66
	v_lshl_add_u64 v[68:69], v[68:69], 0, v[138:139]
	v_fmamk_f32 v70, v70, 0x3a800000, v161
	v_mul_f32_e32 v71, 0x4b800000, v70
	v_cmp_gt_f32_e32 vcc, s53, v70
	s_nop 1
	v_cndmask_b32_e32 v70, v70, v71, vcc
	v_rsq_f32_e32 v72, v70
	v_lshl_add_u64 v[70:71], v[66:67], 2, s[12:13]
	v_mul_f32_e32 v73, 0x45800000, v72
	v_cndmask_b32_e32 v72, v72, v73, vcc
	v_mul_f32_e32 v62, v62, v72
	v_mul_f32_e32 v63, v63, v72
	v_mul_f32_e32 v64, v64, v72
	v_mul_f32_e32 v65, v65, v72
	v_mul_f32_e32 v58, v58, v72
	v_mul_f32_e32 v59, v59, v72
	v_mul_f32_e32 v60, v60, v72
	v_mul_f32_e32 v61, v61, v72
	v_mul_f32_e32 v73, v54, v72
	v_mul_f32_e32 v74, v55, v72
	v_mul_f32_e32 v75, v56, v72
	v_mul_f32_e32 v76, v57, v72
	v_mul_f32_e32 v77, v50, v72
	v_mul_f32_e32 v78, v51, v72
	v_mul_f32_e32 v79, v52, v72
	v_mul_f32_e32 v72, v53, v72
	v_max_f32_e32 v50, 0, v62
	v_max_f32_e32 v51, 0, v63
	v_max_f32_e32 v52, 0, v64
	v_max_f32_e32 v53, 0, v65
	v_max_f32_e32 v54, 0, v58
	v_max_f32_e32 v55, 0, v59
	v_max_f32_e32 v56, 0, v60
	v_max_f32_e32 v57, 0, v61
	v_max_f32_e32 v58, 0, v73
	v_max_f32_e32 v59, 0, v74
	v_max_f32_e32 v60, 0, v75
	v_max_f32_e32 v61, 0, v76
	v_max_f32_e32 v62, 0, v77
	v_max_f32_e32 v63, 0, v78
	v_max_f32_e32 v64, 0, v79
	v_max_f32_e32 v65, 0, v72
	v_pk_mul_f32 v[50:51], v[50:51], v[50:51]
	v_pk_mul_f32 v[52:53], v[52:53], v[52:53]
	v_pk_mul_f32 v[54:55], v[54:55], v[54:55]
	v_pk_mul_f32 v[56:57], v[56:57], v[56:57]
	v_pk_mul_f32 v[58:59], v[58:59], v[58:59]
	v_pk_mul_f32 v[60:61], v[60:61], v[60:61]
	v_pk_mul_f32 v[62:63], v[62:63], v[62:63]
	v_pk_mul_f32 v[64:65], v[64:65], v[64:65]
	v_cvt_pk_bf16_f32 v50, v50, v51
	v_cvt_pk_bf16_f32 v51, v52, v53
	v_cvt_pk_bf16_f32 v52, v54, v55
	v_cvt_pk_bf16_f32 v53, v56, v57
	v_cvt_pk_bf16_f32 v54, v58, v59
	v_cvt_pk_bf16_f32 v55, v60, v61
	v_cvt_pk_bf16_f32 v56, v62, v63
	v_cvt_pk_bf16_f32 v57, v64, v65
	v_permlane16_swap_b32_e32 v50, v52
	v_permlane16_swap_b32_e32 v51, v53
	v_permlane16_swap_b32_e32 v54, v56
	v_permlane16_swap_b32_e32 v55, v57
	global_store_dwordx4 v[68:69], v[50:53], off
	global_store_dwordx4 v[68:69], v[54:57], off offset:256
	s_nop 1
	v_mov_b32_e32 v54, v180
	v_lshlrev_b64 v[52:53], 13, v[66:67]
	v_add_u32_e32 v50, 0xa0, v140
	v_lshl_add_u64 v[52:53], s[10:11], 0, v[52:53]
	v_ashrrev_i32_e32 v51, 31, v50
	v_lshl_add_u64 v[52:53], v[52:53], 0, v[138:139]
	v_fmamk_f32 v54, v54, 0x3a800000, v161
	v_mul_f32_e32 v55, 0x4b800000, v54
	v_cmp_gt_f32_e32 vcc, s53, v54
	s_nop 1
	v_cndmask_b32_e32 v54, v54, v55, vcc
	v_rsq_f32_e32 v56, v54
	v_lshl_add_u64 v[54:55], v[50:51], 2, s[12:13]
	v_mul_f32_e32 v57, 0x45800000, v56
	v_cndmask_b32_e32 v56, v56, v57, vcc
	v_mul_f32_e32 v46, v46, v56
	v_mul_f32_e32 v47, v47, v56
	v_mul_f32_e32 v48, v48, v56
	v_mul_f32_e32 v49, v49, v56
	v_mul_f32_e32 v42, v42, v56
	v_mul_f32_e32 v43, v43, v56
	v_mul_f32_e32 v44, v44, v56
	v_mul_f32_e32 v45, v45, v56
	v_mul_f32_e32 v57, v38, v56
	v_mul_f32_e32 v58, v39, v56
	v_mul_f32_e32 v59, v40, v56
	v_mul_f32_e32 v60, v41, v56
	v_mul_f32_e32 v61, v34, v56
	v_mul_f32_e32 v62, v35, v56
	v_mul_f32_e32 v63, v36, v56
	v_mul_f32_e32 v56, v37, v56
	v_max_f32_e32 v34, 0, v46
	v_max_f32_e32 v35, 0, v47
	v_max_f32_e32 v36, 0, v48
	v_max_f32_e32 v37, 0, v49
	v_max_f32_e32 v38, 0, v42
	v_max_f32_e32 v39, 0, v43
	v_max_f32_e32 v40, 0, v44
	v_max_f32_e32 v41, 0, v45
	v_max_f32_e32 v42, 0, v57
	v_max_f32_e32 v43, 0, v58
	v_max_f32_e32 v44, 0, v59
	v_max_f32_e32 v45, 0, v60
	v_max_f32_e32 v46, 0, v61
	v_max_f32_e32 v47, 0, v62
	v_max_f32_e32 v48, 0, v63
	v_max_f32_e32 v49, 0, v56
; #define PG8_WAIT_V(n) asm volatile("s_waitcnt vmcnt(" #n ")" ::: "memory")
; #define PG8_BAR __builtin_amdgcn_s_barrier()
; template <class Epi, class Sched>
; __device__ __forceinline__ void gemm_phase(PG8_LAS unsigned char* lds, const Gemm g, const Sched& S, const Epi& E) {
;     ...
;         E(acc, cur, wr, wc, fr, fq);
;         if (!has_next) break;
; #pragma unroll
;         for (int a = 0; a < 2; ++a)
; #pragma unroll
;             for (int b = 0; b < 2; ++b)
; #pragma unroll
;                 for (int m = 0; m < 4; ++m)
; #pragma unroll
;                     for (int n = 0; n < 2; ++n) acc[a][b][m][n] = (f32x4){0.f, 0.f, 0.f, 0.f};
;         cur = nxt; cA = nA; cB = nB; ++ui;
;     }
;     PG8_WAIT_V(0);
;     if (wr == 0) PG8_BAR;
;     PG8_BAR;
;   __device__ __forceinline__ void operator()(const acc8_t& acc, const pg8::Unit& u, int wr, int wc, int fr, int fq) const {
;     ...
;         const size_t token = EPI_TOKEN(u, ai, m);
;         const float rs = rsqrtf(rss[token] * (1.f / 1024.f) + 1e-6f);
; #pragma unroll
;         for (int bj = 0; bj < 2; bj++)
; #pragma unroll
;           for (int n = 0; n < 2; n++) {
;             const int f = EPI_COL(u, bj, n);
;             const float v0 = fmaxf(acc[ai][bj][m][n][0] * rs, 0.f), v1 = fmaxf(acc[ai][bj][m][n][1] * rs, 0.f);
;             const float v2 = fmaxf(acc[ai][bj][m][n][2] * rs, 0.f), v3 = fmaxf(acc[ai][bj][m][n][3] * rs, 0.f);
;             uint2 o; o.x = pack2(v0 * v0, v1 * v1); o.y = pack2(v2 * v2, v3 * v3);
;             *(uint2*)(H + token * 4096 + f) = o;
	v_pk_mul_f32 v[34:35], v[34:35], v[34:35]
	v_pk_mul_f32 v[36:37], v[36:37], v[36:37]
	v_pk_mul_f32 v[38:39], v[38:39], v[38:39]
	v_pk_mul_f32 v[40:41], v[40:41], v[40:41]
	v_pk_mul_f32 v[42:43], v[42:43], v[42:43]
	v_pk_mul_f32 v[44:45], v[44:45], v[44:45]
	v_pk_mul_f32 v[46:47], v[46:47], v[46:47]
	v_pk_mul_f32 v[48:49], v[48:49], v[48:49]
	v_cvt_pk_bf16_f32 v34, v34, v35
	v_cvt_pk_bf16_f32 v35, v36, v37
	v_cvt_pk_bf16_f32 v36, v38, v39
	v_cvt_pk_bf16_f32 v37, v40, v41
	v_cvt_pk_bf16_f32 v38, v42, v43
	v_cvt_pk_bf16_f32 v39, v44, v45
	v_cvt_pk_bf16_f32 v40, v46, v47
	v_cvt_pk_bf16_f32 v41, v48, v49
	v_permlane16_swap_b32_e32 v34, v36
	v_permlane16_swap_b32_e32 v35, v37
	v_permlane16_swap_b32_e32 v38, v40
	v_permlane16_swap_b32_e32 v39, v41
	global_store_dwordx4 v[52:53], v[34:37], off
	global_store_dwordx4 v[52:53], v[38:41], off offset:256
	s_nop 1
	v_mov_b32_e32 v38, v181
	v_lshlrev_b64 v[36:37], 13, v[50:51]
	v_add_u32_e32 v34, 0xb0, v140
	v_lshl_add_u64 v[36:37], s[10:11], 0, v[36:37]
	v_ashrrev_i32_e32 v35, 31, v34
	v_lshl_add_u64 v[36:37], v[36:37], 0, v[138:139]
	v_fmamk_f32 v38, v38, 0x3a800000, v161
	v_mul_f32_e32 v39, 0x4b800000, v38
	v_cmp_gt_f32_e32 vcc, s53, v38
	s_nop 1
	v_cndmask_b32_e32 v38, v38, v39, vcc
	v_rsq_f32_e32 v40, v38
	v_lshl_add_u64 v[38:39], v[34:35], 2, s[12:13]
	v_mul_f32_e32 v41, 0x45800000, v40
	v_cndmask_b32_e32 v40, v40, v41, vcc
	v_mul_f32_e32 v30, v30, v40
	v_mul_f32_e32 v31, v31, v40
	v_mul_f32_e32 v32, v32, v40
	v_mul_f32_e32 v33, v33, v40
	v_mul_f32_e32 v26, v26, v40
	v_mul_f32_e32 v27, v27, v40
	v_mul_f32_e32 v28, v28, v40
	v_mul_f32_e32 v29, v29, v40
	v_mul_f32_e32 v41, v22, v40
	v_mul_f32_e32 v42, v23, v40
	v_mul_f32_e32 v43, v24, v40
	v_mul_f32_e32 v44, v25, v40
	v_mul_f32_e32 v45, v18, v40
	v_mul_f32_e32 v46, v19, v40
	v_mul_f32_e32 v47, v20, v40
	v_mul_f32_e32 v40, v21, v40
	v_max_f32_e32 v18, 0, v30
	v_max_f32_e32 v19, 0, v31
	v_max_f32_e32 v20, 0, v32
	v_max_f32_e32 v21, 0, v33
	v_max_f32_e32 v22, 0, v26
	v_max_f32_e32 v23, 0, v27
	v_max_f32_e32 v24, 0, v28
	v_max_f32_e32 v25, 0, v29
	v_max_f32_e32 v26, 0, v41
	v_max_f32_e32 v27, 0, v42
	v_max_f32_e32 v28, 0, v43
	v_max_f32_e32 v29, 0, v44
	v_max_f32_e32 v30, 0, v45
	v_max_f32_e32 v31, 0, v46
	v_max_f32_e32 v32, 0, v47
	v_max_f32_e32 v33, 0, v40
	v_pk_mul_f32 v[18:19], v[18:19], v[18:19]
	v_pk_mul_f32 v[20:21], v[20:21], v[20:21]
	v_pk_mul_f32 v[22:23], v[22:23], v[22:23]
	v_pk_mul_f32 v[24:25], v[24:25], v[24:25]
	v_pk_mul_f32 v[26:27], v[26:27], v[26:27]
	v_pk_mul_f32 v[28:29], v[28:29], v[28:29]
	v_pk_mul_f32 v[30:31], v[30:31], v[30:31]
	v_pk_mul_f32 v[32:33], v[32:33], v[32:33]
	v_cvt_pk_bf16_f32 v18, v18, v19
	v_cvt_pk_bf16_f32 v19, v20, v21
	v_cvt_pk_bf16_f32 v20, v22, v23
	v_cvt_pk_bf16_f32 v21, v24, v25
	v_cvt_pk_bf16_f32 v22, v26, v27
	v_cvt_pk_bf16_f32 v23, v28, v29
	v_cvt_pk_bf16_f32 v24, v30, v31
	v_cvt_pk_bf16_f32 v25, v32, v33
	v_permlane16_swap_b32_e32 v18, v20
	v_permlane16_swap_b32_e32 v19, v21
	v_permlane16_swap_b32_e32 v22, v24
	v_permlane16_swap_b32_e32 v23, v25
	global_store_dwordx4 v[36:37], v[18:21], off
	global_store_dwordx4 v[36:37], v[22:25], off offset:256
	s_nop 1
	v_mov_b32_e32 v18, v182
	s_and_b64 vcc, exec, s[4:5]
	v_fmamk_f32 v18, v18, 0x3a800000, v161
	v_mul_f32_e32 v19, 0x4b800000, v18
	v_cmp_gt_f32_e64 s[4:5], s53, v18
	s_nop 1
	v_cndmask_b32_e64 v18, v18, v19, s[4:5]
	v_rsq_f32_e32 v20, v18
	v_lshlrev_b64 v[18:19], 13, v[34:35]
	v_lshl_add_u64 v[18:19], s[10:11], 0, v[18:19]
	v_lshl_add_u64 v[18:19], v[18:19], 0, v[138:139]
	v_mul_f32_e32 v21, 0x45800000, v20
	v_cndmask_b32_e64 v20, v20, v21, s[4:5]
	v_mul_f32_e32 v14, v14, v20
	v_mul_f32_e32 v15, v15, v20
	v_mul_f32_e32 v16, v16, v20
	v_mul_f32_e32 v17, v17, v20
	v_mul_f32_e32 v10, v10, v20
	v_mul_f32_e32 v11, v11, v20
	v_mul_f32_e32 v12, v12, v20
	v_mul_f32_e32 v13, v13, v20
	v_mul_f32_e32 v21, v6, v20
	v_mul_f32_e32 v22, v7, v20
	v_mul_f32_e32 v23, v8, v20
	v_mul_f32_e32 v24, v9, v20
	v_mul_f32_e32 v25, v2, v20
	v_mul_f32_e32 v26, v3, v20
	v_mul_f32_e32 v27, v4, v20
	v_mul_f32_e32 v20, v5, v20
	v_max_f32_e32 v2, 0, v14
	v_max_f32_e32 v3, 0, v15
	v_max_f32_e32 v4, 0, v16
	v_max_f32_e32 v5, 0, v17
	v_max_f32_e32 v6, 0, v10
	v_max_f32_e32 v7, 0, v11
	v_max_f32_e32 v8, 0, v12
	v_max_f32_e32 v9, 0, v13
	v_max_f32_e32 v10, 0, v21
	v_max_f32_e32 v11, 0, v22
	v_max_f32_e32 v12, 0, v23
	v_max_f32_e32 v13, 0, v24
	v_max_f32_e32 v14, 0, v25
	v_max_f32_e32 v15, 0, v26
	v_max_f32_e32 v16, 0, v27
	v_max_f32_e32 v17, 0, v20
	v_pk_mul_f32 v[2:3], v[2:3], v[2:3]
	v_pk_mul_f32 v[4:5], v[4:5], v[4:5]
	v_pk_mul_f32 v[6:7], v[6:7], v[6:7]
	v_pk_mul_f32 v[8:9], v[8:9], v[8:9]
	v_pk_mul_f32 v[10:11], v[10:11], v[10:11]
	v_pk_mul_f32 v[12:13], v[12:13], v[12:13]
	v_pk_mul_f32 v[14:15], v[14:15], v[14:15]
	v_pk_mul_f32 v[16:17], v[16:17], v[16:17]
	v_cvt_pk_bf16_f32 v2, v2, v3
	v_cvt_pk_bf16_f32 v3, v4, v5
	v_cvt_pk_bf16_f32 v4, v6, v7
	v_cvt_pk_bf16_f32 v5, v8, v9
	v_cvt_pk_bf16_f32 v6, v10, v11
	v_cvt_pk_bf16_f32 v7, v12, v13
	v_cvt_pk_bf16_f32 v8, v14, v15
	v_cvt_pk_bf16_f32 v9, v16, v17
	v_permlane16_swap_b32_e32 v2, v4
	v_permlane16_swap_b32_e32 v3, v5
	v_permlane16_swap_b32_e32 v6, v8
	v_permlane16_swap_b32_e32 v7, v9
	global_store_dwordx4 v[18:19], v[2:5], off
	global_store_dwordx4 v[18:19], v[6:9], off offset:256
	s_nop 1
	s_cbranch_vccz .LBB0_794
	s_waitcnt vmcnt(0)
	s_cmpk_gt_u32 s33, 0xff
	s_cbranch_scc1 .LBB0_804
	s_barrier
